# cmp2_task kv0 epilogue: 16 gain loads hoisted ahead of the sum-of-squares chain; hgrn_u_task: 20 fragment loads issued up front with per-fragment vmcnt waits instead of load-wait-MFMA round trips
# speedup vs baseline: 1.0090x; 1.0050x over previous
; DI float xhalf_sum(float v) { const auto r = __builtin_amdgcn_permlane32_swap(__float_as_uint(v), __float_as_uint(v), false, false); return __uint_as_float(r[0]) + __uint_as_float(r[1]); }
; DI void st_bf16x4(bf16_t* p, f32x4 v) { u32x2 o; o.x = pk2e(v[0], v[1]); o.y = pk2e(v[2], v[3]); *(u32x2*)p = o; }
; DI void cmp2_task(const Params& p, int e, int kv, int rt) {
;     ...
;   if (kv == 0) {
;     float ss = 0.f;
; #pragma unroll
;     for (int dt = 0; dt < 4; ++dt)
; #pragma unroll
;       for (int i = 0; i < 16; ++i) ss += acc[dt][i] * acc[dt][i];
;     ss = xhalf_sum(ss);
;     const float rs = rsqrtf(ss * (1.f / 128.f) + EPS_);
;     const float* gn = p.in[16] + (e * 3 + 0) * 128;
;     bf16_t* orow = (bf16_t*)(p.ws + O_KCMP) + (size_t)row * 128;
; #pragma unroll
;     for (int dt = 0; dt < 4; ++dt)
; #pragma unroll
;       for (int q = 0; q < 4; ++q) {
;         const int d0 = dt * 32 + q * 8 + 4 * g;
;         const f32x4 gg = *(const f32x4*)(gn + d0);
;         f32x4 v; for (int e2 = 0; e2 < 4; ++e2) v[e2] = acc[dt][q * 4 + e2] * rs * gg[e2];
;         st_bf16x4(orow + d0, v);
;       }
.LBB0_305:
	s_andn2_saveexec_b64 s[10:11], s[10:11]
	s_cbranch_execz .LBB0_300
	v_lshlrev_b32_e32 v107, 4, v72
	global_load_dwordx4 v[108:111], v107, s[4:5]
	global_load_dwordx4 v[112:115], v107, s[4:5] offset:32
	global_load_dwordx4 v[116:119], v107, s[4:5] offset:64
	global_load_dwordx4 v[120:123], v107, s[4:5] offset:96
	global_load_dwordx4 v[124:127], v107, s[4:5] offset:128
	global_load_dwordx4 v[128:131], v107, s[4:5] offset:160
	global_load_dwordx4 v[132:135], v107, s[4:5] offset:192
	global_load_dwordx4 v[136:139], v107, s[4:5] offset:224
	global_load_dwordx4 v[140:143], v107, s[4:5] offset:256
	global_load_dwordx4 v[144:147], v107, s[4:5] offset:288
	global_load_dwordx4 v[148:151], v107, s[4:5] offset:320
	global_load_dwordx4 v[152:155], v107, s[4:5] offset:352
	global_load_dwordx4 v[156:159], v107, s[4:5] offset:384
	global_load_dwordx4 v[160:163], v107, s[4:5] offset:416
	global_load_dwordx4 v[164:167], v107, s[4:5] offset:448
	global_load_dwordx4 v[168:171], v107, s[4:5] offset:480
	v_mul_f32_e32 v0, v51, v51
	v_fmac_f32_e32 v0, v50, v50
	v_fmac_f32_e32 v0, v52, v52
	v_fmac_f32_e32 v0, v53, v53
	v_fmac_f32_e32 v0, v54, v54
	v_fmac_f32_e32 v0, v55, v55
	v_fmac_f32_e32 v0, v56, v56
	v_fmac_f32_e32 v0, v57, v57
	v_fmac_f32_e32 v0, v58, v58
	v_fmac_f32_e32 v0, v59, v59
	v_fmac_f32_e32 v0, v60, v60
	v_fmac_f32_e32 v0, v61, v61
	v_fmac_f32_e32 v0, v62, v62
	v_fmac_f32_e32 v0, v63, v63
	v_fmac_f32_e32 v0, v64, v64
	v_fmac_f32_e32 v0, v65, v65
	v_fmac_f32_e32 v0, v34, v34
	v_fmac_f32_e32 v0, v35, v35
	v_fmac_f32_e32 v0, v36, v36
	v_fmac_f32_e32 v0, v37, v37
	v_fmac_f32_e32 v0, v38, v38
	v_fmac_f32_e32 v0, v39, v39
	v_fmac_f32_e32 v0, v40, v40
	v_fmac_f32_e32 v0, v41, v41
	v_fmac_f32_e32 v0, v42, v42
	v_fmac_f32_e32 v0, v43, v43
	v_fmac_f32_e32 v0, v44, v44
	v_fmac_f32_e32 v0, v45, v45
	v_fmac_f32_e32 v0, v46, v46
	v_fmac_f32_e32 v0, v47, v47
	v_fmac_f32_e32 v0, v48, v48
	v_fmac_f32_e32 v0, v49, v49
	v_fmac_f32_e32 v0, v18, v18
	v_fmac_f32_e32 v0, v19, v19
	v_fmac_f32_e32 v0, v20, v20
	v_fmac_f32_e32 v0, v21, v21
	v_fmac_f32_e32 v0, v22, v22
	v_fmac_f32_e32 v0, v23, v23
	v_fmac_f32_e32 v0, v24, v24
	v_fmac_f32_e32 v0, v25, v25
	v_fmac_f32_e32 v0, v26, v26
	v_fmac_f32_e32 v0, v27, v27
	v_fmac_f32_e32 v0, v28, v28
	v_fmac_f32_e32 v0, v29, v29
	v_fmac_f32_e32 v0, v30, v30
	v_fmac_f32_e32 v0, v31, v31
	v_fmac_f32_e32 v0, v32, v32
	v_fmac_f32_e32 v0, v33, v33
	v_fmac_f32_e32 v0, v2, v2
	v_fmac_f32_e32 v0, v3, v3
	v_fmac_f32_e32 v0, v4, v4
	v_fmac_f32_e32 v0, v5, v5
	v_fmac_f32_e32 v0, v6, v6
	v_fmac_f32_e32 v0, v7, v7
	v_fmac_f32_e32 v0, v8, v8
	v_fmac_f32_e32 v0, v9, v9
	v_fmac_f32_e32 v0, v10, v10
	v_fmac_f32_e32 v0, v11, v11
	v_pk_mul_f32 v[74:75], v[12:13], v[12:13]
	v_pk_mul_f32 v[70:71], v[14:15], v[14:15]
	v_add_f32_e32 v0, v74, v0
	v_add_f32_e32 v0, v75, v0
	v_add_f32_e32 v0, v70, v0
	v_pk_mul_f32 v[68:69], v[16:17], v[16:17]
	v_add_f32_e32 v0, v71, v0
	v_add_f32_e32 v0, v68, v0
	v_add_f32_e32 v0, v69, v0
	v_mov_b32_e32 v67, v0
	s_nop 1
	v_permlane32_swap_b32_e32 v0, v67
	v_add_f32_e32 v0, v0, v67
	v_fmamk_f32 v0, v0, 0x3c000000, v249
	v_cmp_gt_f32_e32 vcc, s84, v0
	v_mul_f32_e32 v67, 0x4b800000, v0
	v_lshlrev_b32_e32 v73, 4, v72
	v_cndmask_b32_e32 v0, v0, v67, vcc
	v_rsq_f32_e32 v0, v0
	s_nop 0
	v_mul_f32_e32 v67, 0x45800000, v0
	v_cndmask_b32_e32 v0, v0, v67, vcc
	v_lshlrev_b32_e32 v67, 8, v106
	v_lshl_or_b32 v66, v66, 13, v67
	v_mov_b32_e32 v67, v1
	v_lshl_add_u64 v[70:71], s[6:7], 0, v[66:67]
	v_pk_mul_f32 v[50:51], v[50:51], v[0:1] op_sel_hi:[1,0]
	v_pk_mul_f32 v[34:35], v[34:35], v[0:1] op_sel_hi:[1,0]
	v_pk_mul_f32 v[36:37], v[36:37], v[0:1] op_sel_hi:[1,0]
	v_pk_mul_f32 v[38:39], v[38:39], v[0:1] op_sel_hi:[1,0]
	v_pk_mul_f32 v[18:19], v[18:19], v[0:1] op_sel_hi:[1,0]
	v_pk_mul_f32 v[20:21], v[20:21], v[0:1] op_sel_hi:[1,0]
	v_pk_mul_f32 v[22:23], v[22:23], v[0:1] op_sel_hi:[1,0]
	v_pk_mul_f32 v[2:3], v[2:3], v[0:1] op_sel_hi:[1,0]
	v_pk_mul_f32 v[4:5], v[4:5], v[0:1] op_sel_hi:[1,0]
	v_pk_mul_f32 v[6:7], v[6:7], v[0:1] op_sel_hi:[1,0]
	s_waitcnt vmcnt(15)
	v_pk_mul_f32 v[66:67], v[108:109], v[50:51]
	v_pk_mul_f32 v[50:51], v[52:53], v[0:1] op_sel_hi:[1,0]
	v_cvt_pk_bf16_f32 v66, v66, v67
	v_pk_mul_f32 v[52:53], v[110:111], v[50:51]
	v_lshlrev_b32_e32 v50, 3, v72
	v_mov_b32_e32 v51, v1
	v_lshl_add_u64 v[50:51], v[70:71], 0, v[50:51]
	v_cvt_pk_bf16_f32 v67, v52, v53
	global_store_dwordx2 v[50:51], v[66:67], off
	v_pk_mul_f32 v[52:53], v[54:55], v[0:1] op_sel_hi:[1,0]
	v_pk_mul_f32 v[54:55], v[56:57], v[0:1] op_sel_hi:[1,0]
	v_pk_mul_f32 v[56:57], v[58:59], v[0:1] op_sel_hi:[1,0]
	s_waitcnt vmcnt(15)
; DI float xhalf_sum(float v) { const auto r = __builtin_amdgcn_permlane32_swap(__float_as_uint(v), __float_as_uint(v), false, false); return __uint_as_float(r[0]) + __uint_as_float(r[1]); }
; DI void st_bf16x4(bf16_t* p, f32x4 v) { u32x2 o; o.x = pk2e(v[0], v[1]); o.y = pk2e(v[2], v[3]); *(u32x2*)p = o; }
; DI void cmp2_task(const Params& p, int e, int kv, int rt) {
;     ...
;   if (kv == 0) {
;     float ss = 0.f;
; #pragma unroll
;     for (int dt = 0; dt < 4; ++dt)
; #pragma unroll
;       for (int i = 0; i < 16; ++i) ss += acc[dt][i] * acc[dt][i];
;     ss = xhalf_sum(ss);
;     const float rs = rsqrtf(ss * (1.f / 128.f) + EPS_);
;     const float* gn = p.in[16] + (e * 3 + 0) * 128;
;     bf16_t* orow = (bf16_t*)(p.ws + O_KCMP) + (size_t)row * 128;
; #pragma unroll
;     for (int dt = 0; dt < 4; ++dt)
; #pragma unroll
;       for (int q = 0; q < 4; ++q) {
;         const int d0 = dt * 32 + q * 8 + 4 * g;
;         const f32x4 gg = *(const f32x4*)(gn + d0);
;         f32x4 v; for (int e2 = 0; e2 < 4; ++e2) v[e2] = acc[dt][q * 4 + e2] * rs * gg[e2];
;         st_bf16x4(orow + d0, v);
;       }
	v_pk_mul_f32 v[52:53], v[112:113], v[52:53]
	v_pk_mul_f32 v[54:55], v[114:115], v[54:55]
	v_cvt_pk_bf16_f32 v52, v52, v53
	v_cvt_pk_bf16_f32 v53, v54, v55
	global_store_dwordx2 v[50:51], v[52:53], off offset:16
	s_waitcnt vmcnt(15)
	v_pk_mul_f32 v[52:53], v[116:117], v[56:57]
	v_pk_mul_f32 v[56:57], v[60:61], v[0:1] op_sel_hi:[1,0]
	v_cvt_pk_bf16_f32 v52, v52, v53
	v_pk_mul_f32 v[54:55], v[118:119], v[56:57]
	v_pk_mul_f32 v[56:57], v[62:63], v[0:1] op_sel_hi:[1,0]
	v_cvt_pk_bf16_f32 v53, v54, v55
	global_store_dwordx2 v[50:51], v[52:53], off offset:32
	s_waitcnt vmcnt(15)
	v_pk_mul_f32 v[52:53], v[120:121], v[56:57]
	v_pk_mul_f32 v[56:57], v[64:65], v[0:1] op_sel_hi:[1,0]
	v_cvt_pk_bf16_f32 v52, v52, v53
	v_pk_mul_f32 v[54:55], v[122:123], v[56:57]
	s_nop 0
	v_cvt_pk_bf16_f32 v53, v54, v55
	global_store_dwordx2 v[50:51], v[52:53], off offset:48
	s_waitcnt vmcnt(15)
	v_pk_mul_f32 v[34:35], v[124:125], v[34:35]
	v_pk_mul_f32 v[36:37], v[126:127], v[36:37]
	v_cvt_pk_bf16_f32 v34, v34, v35
	v_cvt_pk_bf16_f32 v35, v36, v37
	global_store_dwordx2 v[50:51], v[34:35], off offset:64
	s_waitcnt vmcnt(15)
	v_pk_mul_f32 v[34:35], v[38:39], v[128:129]
	v_pk_mul_f32 v[38:39], v[40:41], v[0:1] op_sel_hi:[1,0]
	v_cvt_pk_bf16_f32 v34, v34, v35
	v_pk_mul_f32 v[36:37], v[38:39], v[130:131]
	v_pk_mul_f32 v[38:39], v[42:43], v[0:1] op_sel_hi:[1,0]
	v_cvt_pk_bf16_f32 v35, v36, v37
	global_store_dwordx2 v[50:51], v[34:35], off offset:80
	s_waitcnt vmcnt(15)
	v_pk_mul_f32 v[34:35], v[38:39], v[132:133]
	v_pk_mul_f32 v[38:39], v[44:45], v[0:1] op_sel_hi:[1,0]
	v_cvt_pk_bf16_f32 v34, v34, v35
	v_pk_mul_f32 v[36:37], v[38:39], v[134:135]
	v_pk_mul_f32 v[38:39], v[46:47], v[0:1] op_sel_hi:[1,0]
	v_cvt_pk_bf16_f32 v35, v36, v37
	global_store_dwordx2 v[50:51], v[34:35], off offset:96
	s_waitcnt vmcnt(15)
	v_pk_mul_f32 v[34:35], v[38:39], v[136:137]
	v_pk_mul_f32 v[38:39], v[48:49], v[0:1] op_sel_hi:[1,0]
	v_cvt_pk_bf16_f32 v34, v34, v35
	v_pk_mul_f32 v[36:37], v[38:39], v[138:139]
	s_nop 0
	v_cvt_pk_bf16_f32 v35, v36, v37
	global_store_dwordx2 v[50:51], v[34:35], off offset:112
	s_waitcnt vmcnt(15)
	v_pk_mul_f32 v[18:19], v[18:19], v[140:141]
	v_pk_mul_f32 v[20:21], v[20:21], v[142:143]
	v_cvt_pk_bf16_f32 v18, v18, v19
	v_cvt_pk_bf16_f32 v19, v20, v21
	global_store_dwordx2 v[50:51], v[18:19], off offset:128
	s_waitcnt vmcnt(15)
	v_pk_mul_f32 v[18:19], v[22:23], v[144:145]
	v_pk_mul_f32 v[22:23], v[24:25], v[0:1] op_sel_hi:[1,0]
	v_cvt_pk_bf16_f32 v18, v18, v19
	v_pk_mul_f32 v[20:21], v[22:23], v[146:147]
	v_pk_mul_f32 v[22:23], v[26:27], v[0:1] op_sel_hi:[1,0]
	v_cvt_pk_bf16_f32 v19, v20, v21
	global_store_dwordx2 v[50:51], v[18:19], off offset:144
	s_waitcnt vmcnt(15)
	v_pk_mul_f32 v[18:19], v[22:23], v[148:149]
	v_pk_mul_f32 v[22:23], v[28:29], v[0:1] op_sel_hi:[1,0]
	v_cvt_pk_bf16_f32 v18, v18, v19
	v_pk_mul_f32 v[20:21], v[22:23], v[150:151]
	v_pk_mul_f32 v[22:23], v[30:31], v[0:1] op_sel_hi:[1,0]
	v_cvt_pk_bf16_f32 v19, v20, v21
	global_store_dwordx2 v[50:51], v[18:19], off offset:160
	s_waitcnt vmcnt(15)
	v_pk_mul_f32 v[18:19], v[22:23], v[152:153]
	v_pk_mul_f32 v[22:23], v[32:33], v[0:1] op_sel_hi:[1,0]
	v_cvt_pk_bf16_f32 v18, v18, v19
	v_pk_mul_f32 v[20:21], v[22:23], v[154:155]
	s_nop 0
	v_cvt_pk_bf16_f32 v19, v20, v21
	global_store_dwordx2 v[50:51], v[18:19], off offset:176
	s_waitcnt vmcnt(15)
	v_pk_mul_f32 v[2:3], v[2:3], v[156:157]
	v_pk_mul_f32 v[4:5], v[4:5], v[158:159]
	v_cvt_pk_bf16_f32 v2, v2, v3
	v_cvt_pk_bf16_f32 v3, v4, v5
	global_store_dwordx2 v[50:51], v[2:3], off offset:192
	s_waitcnt vmcnt(15)
	v_pk_mul_f32 v[2:3], v[6:7], v[160:161]
	v_pk_mul_f32 v[6:7], v[8:9], v[0:1] op_sel_hi:[1,0]
	v_cvt_pk_bf16_f32 v2, v2, v3
	v_pk_mul_f32 v[4:5], v[6:7], v[162:163]
	v_pk_mul_f32 v[6:7], v[10:11], v[0:1] op_sel_hi:[1,0]
	v_cvt_pk_bf16_f32 v3, v4, v5
	global_store_dwordx2 v[50:51], v[2:3], off offset:208
	s_waitcnt vmcnt(15)
	v_pk_mul_f32 v[2:3], v[6:7], v[164:165]
	v_pk_mul_f32 v[6:7], v[12:13], v[0:1] op_sel_hi:[1,0]
	v_cvt_pk_bf16_f32 v2, v2, v3
	v_pk_mul_f32 v[4:5], v[6:7], v[166:167]
	v_pk_mul_f32 v[6:7], v[14:15], v[0:1] op_sel_hi:[1,0]
	v_cvt_pk_bf16_f32 v3, v4, v5
	global_store_dwordx2 v[50:51], v[2:3], off offset:224
	s_waitcnt vmcnt(15)
	v_pk_mul_f32 v[2:3], v[6:7], v[168:169]
	v_pk_mul_f32 v[6:7], v[16:17], v[0:1] op_sel_hi:[1,0]
	v_cvt_pk_bf16_f32 v2, v2, v3
	v_pk_mul_f32 v[4:5], v[6:7], v[170:171]
	s_nop 0
	v_cvt_pk_bf16_f32 v3, v4, v5
	global_store_dwordx2 v[50:51], v[2:3], off offset:240
	s_branch .LBB0_300

; #define TIDX launder((int)threadIdx.x)
; DI bf16_t f2bf(float x) { return (bf16_t)(pk2(x, 0.f) & 0xffffu); }
; DI f32x16 mfma32(bf16x8 a, bf16x8 b, f32x16 c) { return __builtin_amdgcn_mfma_f32_32x32x16_bf16(a, b, c, 0, 0, 0); }
; DI f32x16 zero16() { f32x16 z; for (int i = 0; i < 16; ++i) z[i] = 0.f; return z; }
; DI int crow(int i, int g) { return (i & 3) + 8 * (i >> 2) + 4 * g; }
; DI void hgrn_u_task(const Params& p, int bh, int c, int vt) {
;   const int lane = TIDX & 63, lr = lane & 31, g = lane >> 5;
;   const bf16_t* VT = (const bf16_t*)(p.ws + E_HIT) + (size_t)bh * 128 * T_ + (size_t)(c * 2) * 4096 + (vt * 32 + lr) * 32 + g * 8;
;   const bf16_t* KUT = (const bf16_t*)(p.ws + E_KUT) + (((size_t)bh * 64 + c) * 128 + lr) * 64 + g * 8;
;   f32x16 acc[4];
; #pragma unroll
;   for (int kt = 0; kt < 4; ++kt) acc[kt] = zero16();
; #pragma unroll
;   for (int ts = 0; ts < 4; ++ts) {
;     const bf16x8 a = *(const bf16x8*)(VT + (ts >> 1) * 4096 + (ts & 1) * 16);
; #pragma unroll
;     for (int kt = 0; kt < 4; ++kt) { const bf16x8 bb = *(const bf16x8*)(KUT + (size_t)kt * 32 * 64 + ts * 16); acc[kt] = mfma32(a, bb, acc[kt]); }
;   }
;   bf16_t* U = (bf16_t*)(p.ws + E_U) + ((size_t)bh * 64 + c) * 128 * 128;
; #pragma unroll
;   for (int kt = 0; kt < 4; ++kt)
; #pragma unroll
;     for (int i = 0; i < 16; ++i) U[(size_t)(vt * 32 + crow(i, g)) * 128 + kt * 32 + lr] = f2bf(acc[kt][i]);
.LBB0_339:
	v_mov_b32_e32 v3, v199
	v_ashrrev_i32_e32 v2, 8, v70
	v_bfe_u32 v0, v70, 2, 6
	v_and_b32_e32 v88, 31, v3
	v_bfe_u32 v89, v3, 5, 1
	v_ashrrev_i32_e32 v3, 31, v2
	v_lshlrev_b64 v[4:5], 20, v[2:3]
	v_and_b32_e32 v90, 0x60, v71
	v_lshlrev_b64 v[76:77], 13, v[2:3]
	v_or_b32_e32 v6, v88, v90
	v_lshl_or_b32 v76, v0, 7, v76
	v_lshl_add_u64 v[4:5], s[4:5], 0, v[4:5]
	v_lshlrev_b32_e32 v0, 14, v0
	v_or_b32_e32 v2, v76, v88
	v_mov_b32_e32 v3, v77
	v_lshl_add_u64 v[4:5], v[4:5], 0, v[0:1]
	v_lshlrev_b32_e32 v0, 6, v6
	v_lshlrev_b64 v[2:3], 7, v[2:3]
	v_lshl_add_u64 v[4:5], v[4:5], 0, v[0:1]
	v_lshlrev_b32_e32 v0, 4, v89
	v_lshl_add_u64 v[2:3], s[2:3], 0, v[2:3]
	v_lshl_add_u64 v[78:79], v[4:5], 0, v[0:1]
	v_lshl_add_u64 v[80:81], v[2:3], 0, v[0:1]
	v_lshlrev_b32_e32 v0, 1, v88
	v_add_u32_e32 v70, s10, v70
	v_add_u32_e32 v71, s11, v71
	s_mov_b64 s[12:13], 0x1000
	v_lshl_add_u64 v[82:83], v[80:81], 0, s[12:13]
	s_mov_b64 s[12:13], 0x2000
	v_lshl_add_u64 v[84:85], v[80:81], 0, s[12:13]
	s_mov_b64 s[12:13], 0x3000
	v_lshl_add_u64 v[86:87], v[80:81], 0, s[12:13]
	s_mov_b64 s[12:13], 0x2000
	v_lshl_add_u64 v[172:173], v[78:79], 0, s[12:13]
	s_mov_b64 s[12:13], 0xc0
	global_load_dwordx4 v[92:95], v[78:79], off
	global_load_dwordx4 v[108:111], v[80:81], off
	global_load_dwordx4 v[112:115], v[82:83], off
	global_load_dwordx4 v[116:119], v[84:85], off
	global_load_dwordx4 v[120:123], v[86:87], off
	global_load_dwordx4 v[96:99], v[78:79], off offset:32
	global_load_dwordx4 v[124:127], v[80:81], off offset:32
	global_load_dwordx4 v[128:131], v[82:83], off offset:32
	global_load_dwordx4 v[132:135], v[84:85], off offset:32
	global_load_dwordx4 v[136:139], v[86:87], off offset:32
	global_load_dwordx4 v[100:103], v[172:173], off
	global_load_dwordx4 v[140:143], v[80:81], off offset:64
	global_load_dwordx4 v[144:147], v[82:83], off offset:64
	global_load_dwordx4 v[148:151], v[84:85], off offset:64
	global_load_dwordx4 v[152:155], v[86:87], off offset:64
	global_load_dwordx4 v[104:107], v[172:173], off offset:32
	global_load_dwordx4 v[156:159], v[80:81], off offset:96
	global_load_dwordx4 v[160:163], v[82:83], off offset:96
	global_load_dwordx4 v[164:167], v[84:85], off offset:96
	global_load_dwordx4 v[168:171], v[86:87], off offset:96
	s_waitcnt vmcnt(18)
	v_mfma_f32_32x32x16_bf16 v[50:65], v[92:95], v[108:111], 0
	s_waitcnt vmcnt(17)
	v_mfma_f32_32x32x16_bf16 v[34:49], v[92:95], v[112:115], 0
	s_waitcnt vmcnt(16)
	v_mfma_f32_32x32x16_bf16 v[18:33], v[92:95], v[116:119], 0
	s_waitcnt vmcnt(15)
	v_mfma_f32_32x32x16_bf16 v[2:17], v[92:95], v[120:123], 0
	s_waitcnt vmcnt(13)
	v_mfma_f32_32x32x16_bf16 v[50:65], v[96:99], v[124:127], v[50:65]
	s_waitcnt vmcnt(12)
	v_mfma_f32_32x32x16_bf16 v[34:49], v[96:99], v[128:131], v[34:49]
	s_waitcnt vmcnt(11)
	v_mfma_f32_32x32x16_bf16 v[18:33], v[96:99], v[132:135], v[18:33]
	s_waitcnt vmcnt(10)
	v_mfma_f32_32x32x16_bf16 v[2:17], v[96:99], v[136:139], v[2:17]
	s_waitcnt vmcnt(8)
	v_mfma_f32_32x32x16_bf16 v[50:65], v[100:103], v[140:143], v[50:65]
	s_waitcnt vmcnt(7)
	v_mfma_f32_32x32x16_bf16 v[34:49], v[100:103], v[144:147], v[34:49]
	s_waitcnt vmcnt(6)
	v_mfma_f32_32x32x16_bf16 v[18:33], v[100:103], v[148:151], v[18:33]
	s_waitcnt vmcnt(5)
	v_mfma_f32_32x32x16_bf16 v[2:17], v[100:103], v[152:155], v[2:17]
	s_waitcnt vmcnt(3)
	v_mfma_f32_32x32x16_bf16 v[50:65], v[104:107], v[156:159], v[50:65]
	s_waitcnt vmcnt(2)
	v_mfma_f32_32x32x16_bf16 v[34:49], v[104:107], v[160:163], v[34:49]
	s_waitcnt vmcnt(1)
	v_mfma_f32_32x32x16_bf16 v[18:33], v[104:107], v[164:167], v[18:33]
	s_waitcnt vmcnt(0)
	v_mfma_f32_32x32x16_bf16 v[2:17], v[104:107], v[168:171], v[2:17]
	s_nop 15
	v_cvt_pk_bf16_f32 v50, v50, s0
	v_cvt_pk_bf16_f32 v62, v62, s0
	v_cvt_pk_bf16_f32 v64, v64, s0
	v_cvt_pk_bf16_f32 v34, v34, s0
	v_cvt_pk_bf16_f32 v18, v18, s0
	v_lshlrev_b64 v[66:67], 8, v[76:77]
	v_lshl_add_u64 v[66:67], s[6:7], 0, v[66:67]
	v_lshl_add_u64 v[68:69], v[66:67], 0, v[0:1]
	v_lshlrev_b32_e32 v0, 8, v90
	v_lshl_or_b32 v0, v89, 10, v0
	v_lshl_add_u64 v[66:67], v[68:69], 0, v[0:1]
	global_store_short v[66:67], v50, off
	v_cvt_pk_bf16_f32 v50, v51, s0
	global_store_short v[66:67], v50, off offset:256
	v_cvt_pk_bf16_f32 v50, v52, s0
	global_store_short v[66:67], v50, off offset:512
	v_cvt_pk_bf16_f32 v50, v53, s0
	global_store_short v[66:67], v50, off offset:768
	v_cvt_pk_bf16_f32 v50, v54, s0
	global_store_short v[66:67], v50, off offset:2048
	v_cvt_pk_bf16_f32 v50, v55, s0
	global_store_short v[66:67], v50, off offset:2304
	v_cvt_pk_bf16_f32 v50, v56, s0
	global_store_short v[66:67], v50, off offset:2560
	v_cvt_pk_bf16_f32 v50, v57, s0
	global_store_short v[66:67], v50, off offset:2816
	v_or_b32_e32 v50, 0x1000, v0
	v_mov_b32_e32 v51, v1
	v_cvt_pk_bf16_f32 v54, v58, s0
	v_lshl_add_u64 v[52:53], v[68:69], 0, v[50:51]
	global_store_short v[52:53], v54, off
	v_or_b32_e32 v52, 0x1100, v0
	v_mov_b32_e32 v53, v1
	v_cvt_pk_bf16_f32 v56, v59, s0
	v_lshl_add_u64 v[54:55], v[68:69], 0, v[52:53]
	global_store_short v[54:55], v56, off
	v_or_b32_e32 v54, 0x1200, v0
	v_mov_b32_e32 v55, v1
	v_cvt_pk_bf16_f32 v58, v60, s0
	v_lshl_add_u64 v[56:57], v[68:69], 0, v[54:55]
	global_store_short v[56:57], v58, off
	v_or_b32_e32 v56, 0x1300, v0
	v_mov_b32_e32 v57, v1
	v_cvt_pk_bf16_f32 v60, v61, s0
	v_lshl_add_u64 v[58:59], v[68:69], 0, v[56:57]
	global_store_short v[58:59], v60, off
	v_or_b32_e32 v58, 0x1800, v0
	v_mov_b32_e32 v59, v1
	v_lshl_add_u64 v[60:61], v[68:69], 0, v[58:59]
; DI bf16_t f2bf(float x) { return (bf16_t)(pk2(x, 0.f) & 0xffffu); }
; DI int crow(int i, int g) { return (i & 3) + 8 * (i >> 2) + 4 * g; }
; DI void hgrn_u_task(const Params& p, int bh, int c, int vt) {
;     ...
;   for (int kt = 0; kt < 4; ++kt)
; #pragma unroll
;     for (int i = 0; i < 16; ++i) U[(size_t)(vt * 32 + crow(i, g)) * 128 + kt * 32 + lr] = f2bf(acc[kt][i]);
; DI void run_phase(const Params& p0, int ph) {
;     ...
;           for (int ti = wave * gridDim.x + blockIdx.x; ti < 4096; ti += 8 * gridDim.x) hgrn_u_task(p, ti >> 8, (ti >> 2) & 63, ti & 3);
	global_store_short v[66:67], v34, off offset:64
	v_cvt_pk_bf16_f32 v34, v35, s0
	global_store_short v[60:61], v62, off
	v_or_b32_e32 v60, 0x1900, v0
	v_mov_b32_e32 v61, v1
	global_store_short v[66:67], v34, off offset:320
	v_cvt_pk_bf16_f32 v34, v36, s0
	v_cvt_pk_bf16_f32 v72, v63, s0
	v_lshl_add_u64 v[62:63], v[68:69], 0, v[60:61]
	global_store_short v[66:67], v34, off offset:576
	v_cvt_pk_bf16_f32 v34, v37, s0
	global_store_short v[62:63], v72, off
	v_or_b32_e32 v62, 0x1a00, v0
	v_mov_b32_e32 v63, v1
	global_store_short v[66:67], v34, off offset:832
	v_cvt_pk_bf16_f32 v34, v38, s0
	v_lshl_add_u64 v[72:73], v[68:69], 0, v[62:63]
	v_or_b32_e32 v0, 0x1b00, v0
	global_store_short v[66:67], v34, off offset:2112
	v_cvt_pk_bf16_f32 v34, v39, s0
	global_store_short v[72:73], v64, off
	v_cvt_pk_bf16_f32 v72, v65, s0
	v_lshl_add_u64 v[64:65], v[68:69], 0, v[0:1]
	global_store_short v[66:67], v34, off offset:2368
	v_cvt_pk_bf16_f32 v34, v40, s0
	global_store_short v[64:65], v72, off
	v_lshl_add_u64 v[64:65], v[68:69], 0, 64
	global_store_short v[66:67], v34, off offset:2624
	v_cvt_pk_bf16_f32 v34, v41, s0
	global_store_short v[66:67], v34, off offset:2880
	v_cvt_pk_bf16_f32 v36, v42, s0
	v_lshl_add_u64 v[34:35], v[64:65], 0, v[50:51]
	global_store_short v[34:35], v36, off
	v_cvt_pk_bf16_f32 v36, v43, s0
	v_lshl_add_u64 v[34:35], v[64:65], 0, v[52:53]
	global_store_short v[34:35], v36, off
	v_cvt_pk_bf16_f32 v36, v44, s0
	v_lshl_add_u64 v[34:35], v[64:65], 0, v[54:55]
	global_store_short v[66:67], v18, off offset:128
	v_cvt_pk_bf16_f32 v18, v19, s0
	global_store_short v[34:35], v36, off
	v_cvt_pk_bf16_f32 v36, v45, s0
	v_lshl_add_u64 v[34:35], v[64:65], 0, v[56:57]
	global_store_short v[66:67], v18, off offset:384
	v_cvt_pk_bf16_f32 v18, v20, s0
	global_store_short v[34:35], v36, off
	v_cvt_pk_bf16_f32 v36, v46, s0
	v_lshl_add_u64 v[34:35], v[64:65], 0, v[58:59]
	global_store_short v[66:67], v18, off offset:640
	v_cvt_pk_bf16_f32 v18, v21, s0
	global_store_short v[34:35], v36, off
	v_cvt_pk_bf16_f32 v36, v47, s0
	v_lshl_add_u64 v[34:35], v[64:65], 0, v[60:61]
	global_store_short v[66:67], v18, off offset:896
	v_cvt_pk_bf16_f32 v18, v22, s0
	global_store_short v[34:35], v36, off
	v_cvt_pk_bf16_f32 v36, v48, s0
	v_lshl_add_u64 v[34:35], v[64:65], 0, v[62:63]
	global_store_short v[66:67], v18, off offset:2176
	v_cvt_pk_bf16_f32 v18, v23, s0
	global_store_short v[34:35], v36, off
	v_cvt_pk_bf16_f32 v36, v49, s0
	v_lshl_add_u64 v[34:35], v[64:65], 0, v[0:1]
	global_store_short v[66:67], v18, off offset:2432
	v_cvt_pk_bf16_f32 v18, v24, s0
	global_store_short v[34:35], v36, off
	v_lshl_add_u64 v[34:35], v[68:69], 0, s[16:17]
	global_store_short v[66:67], v18, off offset:2688
	v_cvt_pk_bf16_f32 v18, v25, s0
	global_store_short v[66:67], v18, off offset:2944
	v_cvt_pk_bf16_f32 v20, v26, s0
	v_lshl_add_u64 v[18:19], v[34:35], 0, v[50:51]
	global_store_short v[18:19], v20, off
	v_cvt_pk_bf16_f32 v20, v27, s0
	v_lshl_add_u64 v[18:19], v[34:35], 0, v[52:53]
	v_cvt_pk_bf16_f32 v2, v2, s0
	global_store_short v[18:19], v20, off
	v_cvt_pk_bf16_f32 v20, v28, s0
	v_lshl_add_u64 v[18:19], v[34:35], 0, v[54:55]
	global_store_short v[66:67], v2, off offset:192
	v_cvt_pk_bf16_f32 v2, v3, s0
	global_store_short v[18:19], v20, off
	v_cvt_pk_bf16_f32 v20, v29, s0
	v_lshl_add_u64 v[18:19], v[34:35], 0, v[56:57]
	global_store_short v[66:67], v2, off offset:448
	v_cvt_pk_bf16_f32 v2, v4, s0
	global_store_short v[18:19], v20, off
	v_cvt_pk_bf16_f32 v20, v30, s0
	v_lshl_add_u64 v[18:19], v[34:35], 0, v[58:59]
	global_store_short v[66:67], v2, off offset:704
	v_cvt_pk_bf16_f32 v2, v5, s0
	global_store_short v[18:19], v20, off
	v_cvt_pk_bf16_f32 v20, v31, s0
	v_lshl_add_u64 v[18:19], v[34:35], 0, v[60:61]
	global_store_short v[66:67], v2, off offset:960
	v_cvt_pk_bf16_f32 v2, v6, s0
	global_store_short v[18:19], v20, off
	v_cvt_pk_bf16_f32 v20, v32, s0
	v_lshl_add_u64 v[18:19], v[34:35], 0, v[62:63]
	global_store_short v[66:67], v2, off offset:2240
	v_cvt_pk_bf16_f32 v2, v7, s0
	global_store_short v[18:19], v20, off
	v_cvt_pk_bf16_f32 v20, v33, s0
	v_lshl_add_u64 v[18:19], v[34:35], 0, v[0:1]
	global_store_short v[66:67], v2, off offset:2496
	v_cvt_pk_bf16_f32 v2, v8, s0
	global_store_short v[18:19], v20, off
	v_lshl_add_u64 v[18:19], v[68:69], 0, s[12:13]
	global_store_short v[66:67], v2, off offset:2752
	v_cvt_pk_bf16_f32 v2, v9, s0
	global_store_short v[66:67], v2, off offset:3008
	v_cvt_pk_bf16_f32 v4, v10, s0
	v_lshl_add_u64 v[2:3], v[18:19], 0, v[50:51]
	global_store_short v[2:3], v4, off
	v_cvt_pk_bf16_f32 v4, v11, s0
	v_lshl_add_u64 v[2:3], v[18:19], 0, v[52:53]
	global_store_short v[2:3], v4, off
	v_cvt_pk_bf16_f32 v4, v12, s0
	v_lshl_add_u64 v[2:3], v[18:19], 0, v[54:55]
	global_store_short v[2:3], v4, off
	v_cvt_pk_bf16_f32 v4, v13, s0
	v_lshl_add_u64 v[2:3], v[18:19], 0, v[56:57]
	global_store_short v[2:3], v4, off
	v_cvt_pk_bf16_f32 v4, v14, s0
	v_lshl_add_u64 v[2:3], v[18:19], 0, v[58:59]
	global_store_short v[2:3], v4, off
	v_cvt_pk_bf16_f32 v4, v15, s0
	v_lshl_add_u64 v[2:3], v[18:19], 0, v[60:61]
	s_movk_i32 s12, 0xfff
	global_store_short v[2:3], v4, off
	v_cvt_pk_bf16_f32 v4, v16, s0
	v_lshl_add_u64 v[2:3], v[18:19], 0, v[62:63]
	v_cmp_lt_i32_e32 vcc, s12, v70
	global_store_short v[2:3], v4, off
	v_cvt_pk_bf16_f32 v4, v17, s0
	v_lshl_add_u64 v[2:3], v[18:19], 0, v[0:1]
	s_or_b64 s[8:9], vcc, s[8:9]
	global_store_short v[2:3], v4, off
	s_andn2_b64 exec, exec, s[8:9]
	s_cbranch_execnz .LBB0_339
